# sample conv-mixer item: 17 loads in flight (was 15 serialized round trips)
# speedup vs baseline: 1.0632x; 1.0026x over previous
; __device__ __forceinline__ unsigned cvt_pk_bf16(float lo, float hi) { unsigned r; asm volatile("v_cvt_pk_bf16_f32 %0, %1, %2" : "=v"(r) : "v"(lo), "v"(hi)); return r; }
; #define state_conv ((const float*)KPTR(2))
; __global__ void __launch_bounds__(NTHR, 2) fwd_kernel(Args a) {
;     ...
;             for (int idx = gt; idx < NS * 256; idx += NGT) { const int s = idx >> 8, c4 = (idx & 255) * 4; const int row = MP + s;
;                 const f32x4 u0 = prs_sum4(PRS, s, 1024 + c4) * prs_sum4(PRS, s, 2048 + c4), bgf = prs_sum4(PRS, s, c4);
;                 const float* sp = state_conv + ((size_t)l * NS + s) * 2 * CONVD + c4; const f32x4 u2 = *(const f32x4*)sp, u1 = *(const f32x4*)(sp + CONVD);
;                 float* op = out + O_CS + ((size_t)l * NS + s) * 2 * CONVD + c4; *(f32x4*)op = u1; *(f32x4*)(op + CONVD) = u0;
;                 const f32x4 w0 = *(const f32x4*)(cw + c4), w1 = *(const f32x4*)(cw + CONVD + c4), w2v = *(const f32x4*)(cw + 2 * CONVD + c4);
;                 const f32x4 cu = (u2 * w0 + u1 * w1 + u0 * w2v) * bgf;
;                 u32x2 w; w.x = cvt_pk_bf16(cu.x, cu.y); w.y = cvt_pk_bf16(cu.z, cu.w);
;                 *(u32x2*)(Y + (size_t)row * DM + c4) = w; }
.LBB0_375:
	v_and_b32_e32 v2, 0x3fc, v125
	v_ashrrev_i32_e32 v1, 8, v124
	v_lshlrev_b32_e32 v168, 2, v2
	v_mov_b32_e32 v9, 0x6400
	v_mad_u32_u24 v5, v1, v9, v168
	v_lshl_add_u32 v7, v1, 13, v168
	v_lshlrev_b32_e32 v8, 12, v1
	v_lshl_add_u32 v8, v2, 1, v8
	s_add_u32 s98, s34, 0x1000
	s_addc_u32 s99, s35, 0
	global_load_dwordx4 v[78:81], v5, s[98:99]
	s_add_u32 s98, s34, 0x321000
	s_addc_u32 s99, s35, 0
	global_load_dwordx4 v[82:85], v5, s[98:99]
	s_add_u32 s98, s34, 0x641000
	s_addc_u32 s99, s35, 0
	global_load_dwordx4 v[86:89], v5, s[98:99]
	s_add_u32 s98, s34, 0x961000
	s_addc_u32 s99, s35, 0
	global_load_dwordx4 v[90:93], v5, s[98:99]
	s_add_u32 s98, s34, 0x2000
	s_addc_u32 s99, s35, 0
	global_load_dwordx4 v[94:97], v5, s[98:99]
	s_add_u32 s98, s34, 0x322000
	s_addc_u32 s99, s35, 0
	global_load_dwordx4 v[98:101], v5, s[98:99]
	s_add_u32 s98, s34, 0x642000
	s_addc_u32 s99, s35, 0
	global_load_dwordx4 v[102:105], v5, s[98:99]
	s_add_u32 s98, s34, 0x962000
	s_addc_u32 s99, s35, 0
	global_load_dwordx4 v[128:131], v5, s[98:99]
	global_load_dwordx4 v[132:135], v5, s[34:35]
	s_add_u32 s98, s34, 0x320000
	s_addc_u32 s99, s35, 0
	global_load_dwordx4 v[136:139], v5, s[98:99]
	s_add_u32 s98, s34, 0x640000
	s_addc_u32 s99, s35, 0
	global_load_dwordx4 v[140:143], v5, s[98:99]
	s_add_u32 s98, s34, 0x960000
	s_addc_u32 s99, s35, 0
	global_load_dwordx4 v[144:147], v5, s[98:99]
	s_lshl_b32 s100, s28, 2
	s_add_u32 s98, s26, s100
	s_addc_u32 s99, s27, 0
	global_load_dwordx4 v[148:151], v7, s[98:99]
	s_add_u32 s98, s98, 0x1000
	s_addc_u32 s99, s99, 0
	global_load_dwordx4 v[152:155], v7, s[98:99]
	global_load_dwordx4 v[156:159], v168, s[2:3]
	global_load_dwordx4 v[160:163], v168, s[4:5]
	global_load_dwordx4 v[164:167], v168, s[22:23]
	v_add_u32_e32 v124, s76, v124
	v_add_u32_e32 v125, s58, v125
	s_add_u32 s100, s38, s100
	s_addc_u32 s101, s39, 0
	s_waitcnt vmcnt(13)
	v_pk_add_f32 v[178:179], v[78:79], 0 op_sel_hi:[1,0]
	v_pk_add_f32 v[180:181], v[80:81], 0 op_sel_hi:[1,0]
	v_pk_add_f32 v[178:179], v[178:179], v[82:83]
	v_pk_add_f32 v[180:181], v[180:181], v[84:85]
	v_pk_add_f32 v[178:179], v[178:179], v[86:87]
	v_pk_add_f32 v[180:181], v[180:181], v[88:89]
	v_pk_add_f32 v[178:179], v[178:179], v[90:91]
	v_pk_add_f32 v[180:181], v[180:181], v[92:93]
	s_waitcnt vmcnt(9)
	v_pk_add_f32 v[182:183], v[94:95], 0 op_sel_hi:[1,0]
	v_pk_add_f32 v[184:185], v[96:97], 0 op_sel_hi:[1,0]
	v_pk_add_f32 v[182:183], v[182:183], v[98:99]
	v_pk_add_f32 v[184:185], v[184:185], v[100:101]
	v_pk_add_f32 v[182:183], v[182:183], v[102:103]
	v_pk_add_f32 v[184:185], v[184:185], v[104:105]
	v_pk_add_f32 v[182:183], v[182:183], v[128:129]
	v_pk_add_f32 v[184:185], v[184:185], v[130:131]
	v_pk_mul_f32 v[178:179], v[178:179], v[182:183]
	v_pk_mul_f32 v[180:181], v[180:181], v[184:185]
	s_waitcnt vmcnt(5)
	v_pk_add_f32 v[186:187], v[132:133], 0 op_sel_hi:[1,0]
	v_pk_add_f32 v[188:189], v[134:135], 0 op_sel_hi:[1,0]
	v_pk_add_f32 v[186:187], v[186:187], v[136:137]
	v_pk_add_f32 v[188:189], v[188:189], v[138:139]
	v_pk_add_f32 v[186:187], v[186:187], v[140:141]
	v_pk_add_f32 v[188:189], v[188:189], v[142:143]
	v_pk_add_f32 v[186:187], v[186:187], v[144:145]
	v_pk_add_f32 v[188:189], v[188:189], v[146:147]
	s_waitcnt vmcnt(3)
	global_store_dwordx4 v7, v[152:155], s[100:101]
	s_add_u32 s98, s100, 0x1000
	s_addc_u32 s99, s101, 0
	global_store_dwordx4 v7, v[178:181], s[98:99]
	s_waitcnt vmcnt(2)
	v_pk_mul_f32 v[190:191], v[154:155], v[162:163]
	v_pk_mul_f32 v[192:193], v[152:153], v[160:161]
	v_pk_fma_f32 v[190:191], v[150:151], v[158:159], v[190:191]
	v_pk_fma_f32 v[192:193], v[148:149], v[156:157], v[192:193]
	v_pk_fma_f32 v[190:191], v[180:181], v[166:167], v[190:191]
	v_pk_fma_f32 v[192:193], v[178:179], v[164:165], v[192:193]
	v_pk_mul_f32 v[190:191], v[188:189], v[190:191]
	v_pk_mul_f32 v[192:193], v[186:187], v[192:193]
	s_movk_i32 s6, 0x7fff
	v_cvt_pk_bf16_f32 v0, v192, v193
	v_cvt_pk_bf16_f32 v1, v190, v191
	s_add_u32 s98, s40, 0x2000000
	s_addc_u32 s99, s41, 0
	v_cmp_lt_i32_e32 vcc, s6, v124
	s_or_b64 s[42:43], vcc, s[42:43]
	global_store_dwordx2 v8, v[0:1], s[98:99]
	s_andn2_b64 exec, exec, s[42:43]
	s_cbranch_execnz .LBB0_375
